# FFN-in output (U, full 1 KiB blocks) stored with nt so the streaming stores do not displace the reused A/B tiles in L2
# speedup vs baseline: 1.0109x; 1.0109x over previous
.LBB0_131:
	v_mul_f32_e32 v136, 0xbfb8aa3b, v165
	v_pk_mul_f32 v[168:169], v[136:137], v[126:127] op_sel_hi:[0,1]
	v_exp_f32_e32 v168, v168
	v_exp_f32_e32 v169, v169
	v_mul_f32_e32 v166, v165, v165
	v_rcp_f32_e32 v166, v166
	v_pk_mul_f32 v[122:123], v[126:127], v[122:123]
	v_pk_mul_f32 v[124:125], v[128:129], v[124:125]
	v_pk_fma_f32 v[168:169], v[168:169], v[166:167], v[166:167] op_sel_hi:[1,0,0]
	s_lshl_b32 s7, s21, 8
	v_rcp_f32_e32 v168, v168
	v_rcp_f32_e32 v169, v169
	s_add_i32 s7, s58, s7
	s_lshl_b32 s9, s20, 2
	s_add_i32 s10, s59, s9
	v_pk_mul_f32 v[122:123], v[168:169], v[122:123]
	v_pk_mul_f32 v[126:127], v[136:137], v[128:129] op_sel_hi:[0,1]
	v_exp_f32_e32 v126, v126
	v_exp_f32_e32 v127, v127
	s_ashr_i32 s38, s7, 4
	s_ashr_i32 s11, s10, 31
	s_ashr_i32 s39, s38, 31
	v_pk_fma_f32 v[126:127], v[126:127], v[166:167], v[166:167] op_sel_hi:[1,0,0]
	s_lshl_b64 s[20:21], s[38:39], 17
	v_rcp_f32_e32 v126, v126
	v_rcp_f32_e32 v127, v127
	s_lshl_b64 s[10:11], s[10:11], 10
	s_add_u32 s9, s33, s20
	s_addc_u32 s13, s96, s21
	v_pk_mul_f32 v[124:125], v[126:127], v[124:125]
	v_pk_mul_f32 v[126:127], v[136:137], v[114:115] op_sel_hi:[0,1]
	v_exp_f32_e32 v126, v126
	v_exp_f32_e32 v127, v127
	v_pk_mul_f32 v[114:115], v[114:115], v[118:119]
	v_mbcnt_lo_u32_b32 v130, -1, 0
	v_mbcnt_hi_u32_b32 v130, -1, v130
	s_add_u32 s20, s9, s10
	v_pk_fma_f32 v[126:127], v[126:127], v[166:167], v[166:167] op_sel_hi:[1,0,0]
	v_lshlrev_b32_e32 v0, 6, v130
	v_rcp_f32_e32 v126, v126
	v_rcp_f32_e32 v127, v127
	v_and_b32_e32 v0, 0x3c0, v0
	v_and_b32_e32 v130, -16, v130
	v_pk_mul_f32 v[120:121], v[116:117], v[120:121]
	v_pk_mul_f32 v[118:119], v[126:127], v[114:115]
	v_pk_mul_f32 v[114:115], v[136:137], v[116:117] op_sel_hi:[0,1]
	v_exp_f32_e32 v114, v114
	v_exp_f32_e32 v115, v115
	s_addc_u32 s21, s13, s11
	v_ashrrev_i32_e32 v131, 31, v130
	v_cvt_pk_bf16_f32 v116, v118, v119
	v_pk_fma_f32 v[114:115], v[114:115], v[166:167], v[166:167] op_sel_hi:[1,0,0]
	v_lshl_add_u64 v[118:119], s[20:21], 0, v[0:1]
	v_rcp_f32_e32 v114, v114
	v_rcp_f32_e32 v115, v115
	v_lshl_add_u64 v[118:119], v[118:119], 0, v[130:131]
	v_pk_mul_f32 v[106:107], v[110:111], v[106:107]
	v_pk_mul_f32 v[108:109], v[112:113], v[108:109]
	v_pk_mul_f32 v[120:121], v[114:115], v[120:121]
	v_cvt_pk_bf16_f32 v114, v122, v123
	v_cvt_pk_bf16_f32 v115, v124, v125
	v_cvt_pk_bf16_f32 v117, v120, v121
	global_store_dwordx4 v[118:119], v[114:117], off nt
	s_or_b32 s20, s38, 1
	s_ashr_i32 s21, s20, 31
	v_mul_f32_e32 v114, 0xbfb8aa3b, v164
	v_pk_mul_f32 v[118:119], v[114:115], v[110:111] op_sel_hi:[0,1]
	v_exp_f32_e32 v118, v118
	v_exp_f32_e32 v119, v119
	v_mul_f32_e32 v116, v164, v164
	v_rcp_f32_e32 v116, v116
	s_lshl_b64 s[20:21], s[20:21], 17
	s_add_u32 s9, s33, s20
	v_pk_fma_f32 v[118:119], v[118:119], v[116:117], v[116:117] op_sel_hi:[1,0,0]
	s_addc_u32 s13, s96, s21
	v_rcp_f32_e32 v118, v118
	v_rcp_f32_e32 v119, v119
	s_add_u32 s20, s9, s10
	v_pk_mul_f32 v[104:105], v[100:101], v[104:105]
	s_addc_u32 s21, s13, s11
	v_pk_mul_f32 v[106:107], v[118:119], v[106:107]
	v_pk_mul_f32 v[110:111], v[114:115], v[112:113] op_sel_hi:[0,1]
	v_exp_f32_e32 v110, v110
	v_exp_f32_e32 v111, v111
	v_pk_mul_f32 v[90:91], v[94:95], v[90:91]
	v_pk_mul_f32 v[92:93], v[96:97], v[92:93]
	v_pk_mul_f32 v[88:89], v[84:85], v[88:89]
	v_pk_fma_f32 v[110:111], v[110:111], v[116:117], v[116:117] op_sel_hi:[1,0,0]
	v_pk_mul_f32 v[74:75], v[78:79], v[74:75]
	v_rcp_f32_e32 v110, v110
	v_rcp_f32_e32 v111, v111
	v_pk_mul_f32 v[76:77], v[80:81], v[76:77]
	v_pk_mul_f32 v[72:73], v[68:69], v[72:73]
	v_pk_mul_f32 v[58:59], v[62:63], v[58:59]
	v_pk_mul_f32 v[108:109], v[110:111], v[108:109]
	v_pk_mul_f32 v[110:111], v[114:115], v[98:99] op_sel_hi:[0,1]
	v_exp_f32_e32 v110, v110
	v_exp_f32_e32 v111, v111
	v_pk_mul_f32 v[98:99], v[98:99], v[102:103]
	v_pk_mul_f32 v[60:61], v[64:65], v[60:61]
	v_pk_mul_f32 v[56:57], v[52:53], v[56:57]
	v_pk_fma_f32 v[110:111], v[110:111], v[116:117], v[116:117] op_sel_hi:[1,0,0]
	v_pk_mul_f32 v[42:43], v[46:47], v[42:43]
	v_rcp_f32_e32 v110, v110
	v_rcp_f32_e32 v111, v111
	v_pk_mul_f32 v[44:45], v[48:49], v[44:45]
	v_pk_mul_f32 v[40:41], v[36:37], v[40:41]
	v_pk_mul_f32 v[26:27], v[30:31], v[26:27]
	v_pk_mul_f32 v[102:103], v[110:111], v[98:99]
	v_pk_mul_f32 v[98:99], v[114:115], v[100:101] op_sel_hi:[0,1]
	v_exp_f32_e32 v98, v98
	v_exp_f32_e32 v99, v99
	v_cvt_pk_bf16_f32 v100, v102, v103
	v_lshl_add_u64 v[102:103], s[20:21], 0, v[0:1]
	v_lshl_add_u64 v[102:103], v[102:103], 0, v[130:131]
	v_pk_fma_f32 v[98:99], v[98:99], v[116:117], v[116:117] op_sel_hi:[1,0,0]
	s_or_b32 s20, s38, 2
	v_rcp_f32_e32 v98, v98
	v_rcp_f32_e32 v99, v99
	s_ashr_i32 s21, s20, 31
	s_lshl_b64 s[20:21], s[20:21], 17
	s_add_u32 s9, s33, s20
	v_pk_mul_f32 v[104:105], v[98:99], v[104:105]
	v_cvt_pk_bf16_f32 v98, v106, v107
	v_cvt_pk_bf16_f32 v99, v108, v109
	v_cvt_pk_bf16_f32 v101, v104, v105
	global_store_dwordx4 v[102:103], v[98:101], off nt
	s_addc_u32 s13, s96, s21
	s_add_u32 s20, s9, s10
	v_mul_f32_e32 v98, 0xbfb8aa3b, v163
	v_pk_mul_f32 v[102:103], v[98:99], v[94:95] op_sel_hi:[0,1]
	v_exp_f32_e32 v102, v102
	v_exp_f32_e32 v103, v103
	v_mul_f32_e32 v100, v163, v163
	v_rcp_f32_e32 v100, v100
	s_addc_u32 s21, s13, s11
	v_pk_mul_f32 v[28:29], v[32:33], v[28:29]
	v_pk_fma_f32 v[102:103], v[102:103], v[100:101], v[100:101] op_sel_hi:[1,0,0]
	v_pk_mul_f32 v[24:25], v[20:21], v[24:25]
	v_rcp_f32_e32 v102, v102
	v_rcp_f32_e32 v103, v103
	v_pk_mul_f32 v[10:11], v[14:15], v[10:11]
	v_pk_mul_f32 v[12:13], v[16:17], v[12:13]
	v_pk_mul_f32 v[2:3], v[6:7], v[2:3]
	v_pk_mul_f32 v[90:91], v[102:103], v[90:91]
	v_pk_mul_f32 v[94:95], v[98:99], v[96:97] op_sel_hi:[0,1]
	v_exp_f32_e32 v94, v94
	v_exp_f32_e32 v95, v95
	v_pk_mul_f32 v[4:5], v[8:9], v[4:5]
	v_pk_fma_f32 v[94:95], v[94:95], v[100:101], v[100:101] op_sel_hi:[1,0,0]
	s_nop 0
	v_rcp_f32_e32 v94, v94
	v_rcp_f32_e32 v95, v95
	s_nop 0
	v_pk_mul_f32 v[92:93], v[94:95], v[92:93]
	v_pk_mul_f32 v[94:95], v[98:99], v[82:83] op_sel_hi:[0,1]
	v_exp_f32_e32 v94, v94
	v_exp_f32_e32 v95, v95
	v_pk_mul_f32 v[82:83], v[82:83], v[86:87]
	v_pk_fma_f32 v[94:95], v[94:95], v[100:101], v[100:101] op_sel_hi:[1,0,0]
	s_nop 0
	v_rcp_f32_e32 v94, v94
	v_rcp_f32_e32 v95, v95
	s_nop 0
	v_pk_mul_f32 v[86:87], v[94:95], v[82:83]
	v_pk_mul_f32 v[82:83], v[98:99], v[84:85] op_sel_hi:[0,1]
	v_exp_f32_e32 v82, v82
	v_exp_f32_e32 v83, v83
	v_cvt_pk_bf16_f32 v84, v86, v87
	v_lshl_add_u64 v[86:87], s[20:21], 0, v[0:1]
	v_lshl_add_u64 v[86:87], v[86:87], 0, v[130:131]
	v_pk_fma_f32 v[82:83], v[82:83], v[100:101], v[100:101] op_sel_hi:[1,0,0]
	s_or_b32 s20, s38, 3
	v_rcp_f32_e32 v82, v82
	v_rcp_f32_e32 v83, v83
	s_ashr_i32 s21, s20, 31
	s_lshl_b64 s[20:21], s[20:21], 17
	s_add_u32 s9, s33, s20
	v_pk_mul_f32 v[88:89], v[82:83], v[88:89]
	v_cvt_pk_bf16_f32 v82, v90, v91
	v_cvt_pk_bf16_f32 v83, v92, v93
	v_cvt_pk_bf16_f32 v85, v88, v89
	global_store_dwordx4 v[86:87], v[82:85], off nt
	s_addc_u32 s13, s96, s21
	s_add_u32 s20, s9, s10
	v_mul_f32_e32 v82, 0xbfb8aa3b, v162
	v_pk_mul_f32 v[86:87], v[82:83], v[78:79] op_sel_hi:[0,1]
	v_exp_f32_e32 v86, v86
	v_exp_f32_e32 v87, v87
	v_mul_f32_e32 v84, v162, v162
	v_rcp_f32_e32 v84, v84
	s_addc_u32 s21, s13, s11
	s_add_i32 s9, s7, 0x80
	v_pk_fma_f32 v[86:87], v[86:87], v[84:85], v[84:85] op_sel_hi:[1,0,0]
	s_nop 0
	v_rcp_f32_e32 v86, v86
	v_rcp_f32_e32 v87, v87
	s_nop 0
	v_pk_mul_f32 v[74:75], v[86:87], v[74:75]
	v_pk_mul_f32 v[78:79], v[82:83], v[80:81] op_sel_hi:[0,1]
	v_exp_f32_e32 v78, v78
	v_exp_f32_e32 v79, v79
	s_nop 0
	v_pk_fma_f32 v[78:79], v[78:79], v[84:85], v[84:85] op_sel_hi:[1,0,0]
	s_nop 0
	v_rcp_f32_e32 v78, v78
	v_rcp_f32_e32 v79, v79
	s_nop 0
	v_pk_mul_f32 v[76:77], v[78:79], v[76:77]
	v_pk_mul_f32 v[78:79], v[82:83], v[66:67] op_sel_hi:[0,1]
	v_exp_f32_e32 v78, v78
	v_exp_f32_e32 v79, v79
	v_pk_mul_f32 v[66:67], v[66:67], v[70:71]
	v_pk_fma_f32 v[78:79], v[78:79], v[84:85], v[84:85] op_sel_hi:[1,0,0]
	s_nop 0
	v_rcp_f32_e32 v78, v78
	v_rcp_f32_e32 v79, v79
	s_nop 0
	v_pk_mul_f32 v[70:71], v[78:79], v[66:67]
	v_pk_mul_f32 v[66:67], v[82:83], v[68:69] op_sel_hi:[0,1]
	v_exp_f32_e32 v66, v66
	v_exp_f32_e32 v67, v67
	v_cvt_pk_bf16_f32 v68, v70, v71
	v_lshl_add_u64 v[70:71], s[20:21], 0, v[0:1]
	v_lshl_add_u64 v[70:71], v[70:71], 0, v[130:131]
	v_pk_fma_f32 v[66:67], v[66:67], v[84:85], v[84:85] op_sel_hi:[1,0,0]
	s_ashr_i32 s20, s9, 4
	v_rcp_f32_e32 v66, v66
	v_rcp_f32_e32 v67, v67
	s_ashr_i32 s21, s20, 31
	s_lshl_b64 s[20:21], s[20:21], 17
	s_add_u32 s9, s33, s20
	v_pk_mul_f32 v[72:73], v[66:67], v[72:73]
	v_cvt_pk_bf16_f32 v66, v74, v75
	v_cvt_pk_bf16_f32 v67, v76, v77
	v_cvt_pk_bf16_f32 v69, v72, v73
	global_store_dwordx4 v[70:71], v[66:69], off nt
	s_addc_u32 s13, s96, s21
	s_add_u32 s20, s9, s10
	v_mul_f32_e32 v66, 0xbfb8aa3b, v161
	v_pk_mul_f32 v[70:71], v[66:67], v[62:63] op_sel_hi:[0,1]
	v_exp_f32_e32 v70, v70
	v_exp_f32_e32 v71, v71
	v_mul_f32_e32 v68, v161, v161
	v_rcp_f32_e32 v68, v68
	s_addc_u32 s21, s13, s11
	s_add_i32 s9, s7, 0x90
	v_pk_fma_f32 v[70:71], v[70:71], v[68:69], v[68:69] op_sel_hi:[1,0,0]
	s_nop 0
	v_rcp_f32_e32 v70, v70
	v_rcp_f32_e32 v71, v71
	s_nop 0
	v_pk_mul_f32 v[58:59], v[70:71], v[58:59]
	v_pk_mul_f32 v[62:63], v[66:67], v[64:65] op_sel_hi:[0,1]
	v_exp_f32_e32 v62, v62
	v_exp_f32_e32 v63, v63
	s_nop 0
	v_pk_fma_f32 v[62:63], v[62:63], v[68:69], v[68:69] op_sel_hi:[1,0,0]
	s_nop 0
	v_rcp_f32_e32 v62, v62
	v_rcp_f32_e32 v63, v63
	s_nop 0
	v_pk_mul_f32 v[60:61], v[62:63], v[60:61]
	v_pk_mul_f32 v[62:63], v[66:67], v[50:51] op_sel_hi:[0,1]
	v_exp_f32_e32 v62, v62
	v_exp_f32_e32 v63, v63
	v_pk_mul_f32 v[50:51], v[50:51], v[54:55]
	v_pk_fma_f32 v[62:63], v[62:63], v[68:69], v[68:69] op_sel_hi:[1,0,0]
	s_nop 0
	v_rcp_f32_e32 v62, v62
	v_rcp_f32_e32 v63, v63
	s_nop 0
	v_pk_mul_f32 v[54:55], v[62:63], v[50:51]
	v_pk_mul_f32 v[50:51], v[66:67], v[52:53] op_sel_hi:[0,1]
	v_exp_f32_e32 v50, v50
	v_exp_f32_e32 v51, v51
	v_cvt_pk_bf16_f32 v52, v54, v55
	v_lshl_add_u64 v[54:55], s[20:21], 0, v[0:1]
	v_lshl_add_u64 v[54:55], v[54:55], 0, v[130:131]
	v_pk_fma_f32 v[50:51], v[50:51], v[68:69], v[68:69] op_sel_hi:[1,0,0]
	s_ashr_i32 s20, s9, 4
	v_rcp_f32_e32 v50, v50
	v_rcp_f32_e32 v51, v51
	s_ashr_i32 s21, s20, 31
	s_lshl_b64 s[20:21], s[20:21], 17
	s_add_u32 s9, s33, s20
	v_pk_mul_f32 v[56:57], v[50:51], v[56:57]
	v_cvt_pk_bf16_f32 v50, v58, v59
	v_cvt_pk_bf16_f32 v51, v60, v61
	v_cvt_pk_bf16_f32 v53, v56, v57
	global_store_dwordx4 v[54:55], v[50:53], off nt
	s_addc_u32 s13, s96, s21
	s_add_u32 s20, s9, s10
	v_mul_f32_e32 v50, 0xbfb8aa3b, v160
	v_pk_mul_f32 v[54:55], v[50:51], v[46:47] op_sel_hi:[0,1]
	v_exp_f32_e32 v54, v54
	v_exp_f32_e32 v55, v55
	v_mul_f32_e32 v52, v160, v160
	v_rcp_f32_e32 v52, v52
	s_addc_u32 s21, s13, s11
	s_add_i32 s9, s7, 0xa0
	v_pk_fma_f32 v[54:55], v[54:55], v[52:53], v[52:53] op_sel_hi:[1,0,0]
	s_nop 0
	v_rcp_f32_e32 v54, v54
	v_rcp_f32_e32 v55, v55
	s_nop 0
	v_pk_mul_f32 v[42:43], v[54:55], v[42:43]
	v_pk_mul_f32 v[46:47], v[50:51], v[48:49] op_sel_hi:[0,1]
	v_exp_f32_e32 v46, v46
	v_exp_f32_e32 v47, v47
	s_nop 0
	v_pk_fma_f32 v[46:47], v[46:47], v[52:53], v[52:53] op_sel_hi:[1,0,0]
	s_nop 0
	v_rcp_f32_e32 v46, v46
	v_rcp_f32_e32 v47, v47
	s_nop 0
	v_pk_mul_f32 v[44:45], v[46:47], v[44:45]
	v_pk_mul_f32 v[46:47], v[50:51], v[34:35] op_sel_hi:[0,1]
	v_exp_f32_e32 v46, v46
	v_exp_f32_e32 v47, v47
	v_pk_mul_f32 v[34:35], v[34:35], v[38:39]
	v_pk_fma_f32 v[46:47], v[46:47], v[52:53], v[52:53] op_sel_hi:[1,0,0]
	s_nop 0
	v_rcp_f32_e32 v46, v46
	v_rcp_f32_e32 v47, v47
	s_nop 0
	v_pk_mul_f32 v[38:39], v[46:47], v[34:35]
	v_pk_mul_f32 v[34:35], v[50:51], v[36:37] op_sel_hi:[0,1]
	v_exp_f32_e32 v34, v34
	v_exp_f32_e32 v35, v35
	v_cvt_pk_bf16_f32 v36, v38, v39
	v_lshl_add_u64 v[38:39], s[20:21], 0, v[0:1]
	v_lshl_add_u64 v[38:39], v[38:39], 0, v[130:131]
	v_pk_fma_f32 v[34:35], v[34:35], v[52:53], v[52:53] op_sel_hi:[1,0,0]
	s_ashr_i32 s20, s9, 4
	v_rcp_f32_e32 v34, v34
	v_rcp_f32_e32 v35, v35
	s_ashr_i32 s21, s20, 31
	s_lshl_b64 s[20:21], s[20:21], 17
	s_add_u32 s9, s33, s20
	v_pk_mul_f32 v[40:41], v[34:35], v[40:41]
	v_cvt_pk_bf16_f32 v34, v42, v43
	v_cvt_pk_bf16_f32 v35, v44, v45
	v_cvt_pk_bf16_f32 v37, v40, v41
	global_store_dwordx4 v[38:39], v[34:37], off nt
	s_addc_u32 s13, s96, s21
	s_add_u32 s20, s9, s10
	v_mul_f32_e32 v34, 0xbfb8aa3b, v154
	v_pk_mul_f32 v[38:39], v[34:35], v[30:31] op_sel_hi:[0,1]
	v_exp_f32_e32 v38, v38
	v_exp_f32_e32 v39, v39
	v_mul_f32_e32 v36, v154, v154
	v_rcp_f32_e32 v36, v36
	s_addc_u32 s21, s13, s11
	s_addk_i32 s7, 0xb0
	v_pk_fma_f32 v[38:39], v[38:39], v[36:37], v[36:37] op_sel_hi:[1,0,0]
	s_nop 0
	v_rcp_f32_e32 v38, v38
	v_rcp_f32_e32 v39, v39
	s_nop 0
	v_pk_mul_f32 v[26:27], v[38:39], v[26:27]
	v_pk_mul_f32 v[30:31], v[34:35], v[32:33] op_sel_hi:[0,1]
	v_exp_f32_e32 v30, v30
	v_exp_f32_e32 v31, v31
	s_nop 0
	v_pk_fma_f32 v[30:31], v[30:31], v[36:37], v[36:37] op_sel_hi:[1,0,0]
	s_nop 0
	v_rcp_f32_e32 v30, v30
	v_rcp_f32_e32 v31, v31
	s_nop 0
	v_pk_mul_f32 v[28:29], v[30:31], v[28:29]
	v_pk_mul_f32 v[30:31], v[34:35], v[18:19] op_sel_hi:[0,1]
	v_exp_f32_e32 v30, v30
	v_exp_f32_e32 v31, v31
	v_pk_mul_f32 v[18:19], v[18:19], v[22:23]
	v_pk_fma_f32 v[30:31], v[30:31], v[36:37], v[36:37] op_sel_hi:[1,0,0]
	s_nop 0
	v_rcp_f32_e32 v30, v30
	v_rcp_f32_e32 v31, v31
	s_nop 0
	v_pk_mul_f32 v[22:23], v[30:31], v[18:19]
	v_pk_mul_f32 v[18:19], v[34:35], v[20:21] op_sel_hi:[0,1]
	v_exp_f32_e32 v18, v18
	v_exp_f32_e32 v19, v19
	v_cvt_pk_bf16_f32 v20, v22, v23
	v_lshl_add_u64 v[22:23], s[20:21], 0, v[0:1]
	v_lshl_add_u64 v[22:23], v[22:23], 0, v[130:131]
	v_pk_fma_f32 v[18:19], v[18:19], v[36:37], v[36:37] op_sel_hi:[1,0,0]
	s_ashr_i32 s20, s7, 4
	v_rcp_f32_e32 v18, v18
	v_rcp_f32_e32 v19, v19
	s_ashr_i32 s21, s20, 31
	s_lshl_b64 s[20:21], s[20:21], 17
	s_add_u32 s7, s33, s20
	v_pk_mul_f32 v[24:25], v[18:19], v[24:25]
	v_cvt_pk_bf16_f32 v18, v26, v27
	v_cvt_pk_bf16_f32 v19, v28, v29
	v_cvt_pk_bf16_f32 v21, v24, v25
	global_store_dwordx4 v[22:23], v[18:21], off nt
	s_addc_u32 s9, s96, s21
	s_add_u32 s10, s7, s10
	v_mul_f32_e32 v18, 0xbfb8aa3b, v151
	v_pk_mul_f32 v[22:23], v[18:19], v[14:15] op_sel_hi:[0,1]
	v_exp_f32_e32 v22, v22
	v_exp_f32_e32 v23, v23
	v_mul_f32_e32 v20, v151, v151
	v_rcp_f32_e32 v20, v20
	s_addc_u32 s11, s9, s11
	s_and_b64 vcc, exec, s[36:37]
	v_pk_fma_f32 v[22:23], v[22:23], v[20:21], v[20:21] op_sel_hi:[1,0,0]
	s_nop 0
	v_rcp_f32_e32 v22, v22
	v_rcp_f32_e32 v23, v23
	s_nop 0
	v_pk_mul_f32 v[10:11], v[22:23], v[10:11]
	v_pk_mul_f32 v[14:15], v[18:19], v[16:17] op_sel_hi:[0,1]
	v_exp_f32_e32 v14, v14
	v_exp_f32_e32 v15, v15
	s_nop 0
	v_pk_fma_f32 v[14:15], v[14:15], v[20:21], v[20:21] op_sel_hi:[1,0,0]
	s_nop 0
	v_rcp_f32_e32 v14, v14
	v_rcp_f32_e32 v15, v15
	s_nop 0
	v_pk_mul_f32 v[12:13], v[14:15], v[12:13]
	v_pk_mul_f32 v[14:15], v[18:19], v[6:7] op_sel_hi:[0,1]
	v_exp_f32_e32 v14, v14
	v_exp_f32_e32 v15, v15
	s_nop 0
	v_pk_fma_f32 v[14:15], v[14:15], v[20:21], v[20:21] op_sel_hi:[1,0,0]
	s_nop 0
	v_rcp_f32_e32 v14, v14
	v_rcp_f32_e32 v15, v15
	s_nop 0
	v_pk_mul_f32 v[6:7], v[14:15], v[2:3]
	v_pk_mul_f32 v[2:3], v[18:19], v[8:9] op_sel_hi:[0,1]
	v_exp_f32_e32 v2, v2
	v_exp_f32_e32 v3, v3
	s_nop 0
	v_pk_fma_f32 v[2:3], v[2:3], v[20:21], v[20:21] op_sel_hi:[1,0,0]
	s_nop 0
	v_rcp_f32_e32 v2, v2
	v_rcp_f32_e32 v3, v3
	s_nop 0
	v_pk_mul_f32 v[8:9], v[2:3], v[4:5]
	v_cvt_pk_bf16_f32 v4, v6, v7
	v_lshl_add_u64 v[6:7], s[10:11], 0, v[0:1]
	v_cvt_pk_bf16_f32 v2, v10, v11
	v_cvt_pk_bf16_f32 v3, v12, v13
	v_cvt_pk_bf16_f32 v5, v8, v9
	v_lshl_add_u64 v[6:7], v[6:7], 0, v[130:131]
	s_mov_b64 s[10:11], -1
	global_store_dwordx4 v[6:7], v[2:5], off nt
	s_cbranch_vccnz .LBB0_118
	s_andn2_b64 vcc, exec, s[0:1]
	s_cbranch_vccnz .LBB0_117
	s_barrier
	s_branch .LBB0_117
